# e21: hand-written HGRN chunk scan - 32 loads up front, fma chain from registers
# speedup vs baseline: 1.0021x; 1.0021x over previous
; __device__ __forceinline__ unsigned cvt_pk_bf16(float lo, float hi) { unsigned r; asm volatile("v_cvt_pk_bf16_f32 %0, %1, %2" : "=v"(r) : "v"(lo), "v"(hi)); return r; }
; #define PHASE_SYNC(id) do { if ((id) != lo) xcd_barrier(bar); } while (0)
; __global__ void __launch_bounds__(512, 2) fwd_kernel(Args a) {
;     ...
;             if (SITE(3) && PHASE_ON(base + 2)) { PHASE_SYNC(base + 2); HG_PTRS
;                 for (int e = vcu * 512 + tid; e < 16 * 8192; e += G * 512) { const int h = e >> 13, k = (e & 8191) >> 6, v2 = (e & 63) * 2;
;                     f32x2 s = {0.f, 0.f}; bf16* p = SB + ((size_t)h * 16 * 128 + k) * 128 + v2; const float* dp = DT + (size_t)h * 16 * 128 + k;
; #pragma unroll 8
;                     for (int c = 0; c < 16; ++c) { const unsigned bw = *(const unsigned*)(p + (size_t)c * 16384); const f32x2 bb = {__uint_as_float(bw << 16), __uint_as_float(bw & 0xffff0000u)}; const float d = dp[c * 128];
;                         *(unsigned*)(p + (size_t)c * 16384) = cvt_pk_bf16(s[0], s[1]); s = s * d + bb; }
;                     *(f32x2*)(out + OFF_HG_P + ((size_t)(j * 16 + h) * 128 + k) * 128 + v2) = s; } }
.LBB0_2257:
	v_lshl_add_u32 v16, s96, 9, v0
	v_cmp_gt_i32_e32 vcc, 0x20000, v16
	s_and_saveexec_b64 s[0:1], vcc
	s_cbranch_execz .LBB0_2262
	s_load_dwordx2 s[2:3], s[94:95], 0xf8
	s_load_dwordx2 s[4:5], s[94:95], 0x100
	v_readlane_b32 s58, v255, 24
	v_readlane_b32 s59, v255, 25
	s_waitcnt lgkmcnt(0)
	s_add_u32 s2, s2, 0x8200000
	s_addc_u32 s3, s3, 0
	s_and_b64 s[58:59], s[58:59], exec
	s_cselect_b32 s6, 16, 0
	s_lshl_b32 s10, s76, 9
	s_add_u32 s62, s4, 0x3ca00000
	s_addc_u32 s63, s5, 0
	s_add_u32 s64, s4, 0x40a00000
	s_addc_u32 s65, s5, 0
	s_mov_b64 s[14:15], 0
.Lscan_loop:
	v_ashrrev_i32_e32 v4, 13, v16
	v_bfe_u32 v5, v16, 6, 7
	v_and_b32_e32 v6, 63, v16
	v_lshlrev_b32_e32 v7, 19, v4
	v_lshl_add_u32 v7, v5, 8, v7
	v_lshl_add_u32 v7, v6, 2, v7
	v_mov_b32_e32 v9, v7
	v_lshlrev_b32_e32 v8, 13, v4
	v_lshl_add_u32 v8, v5, 2, v8
	v_add_u32_e32 v10, 0x1000, v8
	global_load_dword v208, v7, s[62:63]
	v_add_u32_e32 v7, 0x8000, v7
	global_load_dword v209, v7, s[62:63]
	v_add_u32_e32 v7, 0x8000, v7
	global_load_dword v210, v7, s[62:63]
	v_add_u32_e32 v7, 0x8000, v7
	global_load_dword v211, v7, s[62:63]
	v_add_u32_e32 v7, 0x8000, v7
	global_load_dword v212, v7, s[62:63]
	v_add_u32_e32 v7, 0x8000, v7
	global_load_dword v213, v7, s[62:63]
	v_add_u32_e32 v7, 0x8000, v7
	global_load_dword v214, v7, s[62:63]
	v_add_u32_e32 v7, 0x8000, v7
	global_load_dword v215, v7, s[62:63]
	v_add_u32_e32 v7, 0x8000, v7
	global_load_dword v216, v7, s[62:63]
	v_add_u32_e32 v7, 0x8000, v7
	global_load_dword v217, v7, s[62:63]
	v_add_u32_e32 v7, 0x8000, v7
	global_load_dword v218, v7, s[62:63]
	v_add_u32_e32 v7, 0x8000, v7
	global_load_dword v219, v7, s[62:63]
	v_add_u32_e32 v7, 0x8000, v7
	global_load_dword v220, v7, s[62:63]
	v_add_u32_e32 v7, 0x8000, v7
	global_load_dword v221, v7, s[62:63]
	v_add_u32_e32 v7, 0x8000, v7
	global_load_dword v222, v7, s[62:63]
	v_add_u32_e32 v7, 0x8000, v7
	global_load_dword v223, v7, s[62:63]
	global_load_dword v224, v8, s[64:65]
	global_load_dword v225, v8, s[64:65] offset:512
	global_load_dword v226, v8, s[64:65] offset:1024
	global_load_dword v227, v8, s[64:65] offset:1536
	global_load_dword v228, v8, s[64:65] offset:2048
	global_load_dword v229, v8, s[64:65] offset:2560
	global_load_dword v230, v8, s[64:65] offset:3072
	global_load_dword v231, v8, s[64:65] offset:3584
	global_load_dword v232, v10, s[64:65]
	global_load_dword v233, v10, s[64:65] offset:512
	global_load_dword v234, v10, s[64:65] offset:1024
	global_load_dword v235, v10, s[64:65] offset:1536
	global_load_dword v236, v10, s[64:65] offset:2048
	global_load_dword v237, v10, s[64:65] offset:2560
	global_load_dword v238, v10, s[64:65] offset:3072
	global_load_dword v239, v10, s[64:65] offset:3584
	v_mov_b32_e32 v14, 0
	v_mov_b32_e32 v15, 0
	s_waitcnt vmcnt(0)
	v_cvt_pk_bf16_f32 v11, v14, v15
	global_store_dword v9, v11, s[62:63]
	v_add_u32_e32 v9, 0x8000, v9
	v_lshlrev_b32_e32 v12, 16, v208
	v_and_b32_e32 v13, 0xffff0000, v208
	v_fma_f32 v14, v14, v224, v12
	v_fma_f32 v15, v15, v224, v13
	v_cvt_pk_bf16_f32 v17, v14, v15
	global_store_dword v9, v17, s[62:63]
	v_add_u32_e32 v9, 0x8000, v9
	v_lshlrev_b32_e32 v12, 16, v209
	v_and_b32_e32 v13, 0xffff0000, v209
	v_fma_f32 v14, v14, v225, v12
	v_fma_f32 v15, v15, v225, v13
	v_cvt_pk_bf16_f32 v11, v14, v15
	global_store_dword v9, v11, s[62:63]
	v_add_u32_e32 v9, 0x8000, v9
	v_lshlrev_b32_e32 v12, 16, v210
	v_and_b32_e32 v13, 0xffff0000, v210
	v_fma_f32 v14, v14, v226, v12
	v_fma_f32 v15, v15, v226, v13
	v_cvt_pk_bf16_f32 v17, v14, v15
	global_store_dword v9, v17, s[62:63]
	v_add_u32_e32 v9, 0x8000, v9
	v_lshlrev_b32_e32 v12, 16, v211
	v_and_b32_e32 v13, 0xffff0000, v211
	v_fma_f32 v14, v14, v227, v12
	v_fma_f32 v15, v15, v227, v13
	v_cvt_pk_bf16_f32 v11, v14, v15
	global_store_dword v9, v11, s[62:63]
	v_add_u32_e32 v9, 0x8000, v9
	v_lshlrev_b32_e32 v12, 16, v212
	v_and_b32_e32 v13, 0xffff0000, v212
	v_fma_f32 v14, v14, v228, v12
	v_fma_f32 v15, v15, v228, v13
	v_cvt_pk_bf16_f32 v17, v14, v15
	global_store_dword v9, v17, s[62:63]
	v_add_u32_e32 v9, 0x8000, v9
	v_lshlrev_b32_e32 v12, 16, v213
	v_and_b32_e32 v13, 0xffff0000, v213
	v_fma_f32 v14, v14, v229, v12
	v_fma_f32 v15, v15, v229, v13
	v_cvt_pk_bf16_f32 v11, v14, v15
	global_store_dword v9, v11, s[62:63]
	v_add_u32_e32 v9, 0x8000, v9
	v_lshlrev_b32_e32 v12, 16, v214
	v_and_b32_e32 v13, 0xffff0000, v214
	v_fma_f32 v14, v14, v230, v12
	v_fma_f32 v15, v15, v230, v13
	v_cvt_pk_bf16_f32 v17, v14, v15
	global_store_dword v9, v17, s[62:63]
	v_add_u32_e32 v9, 0x8000, v9
	v_lshlrev_b32_e32 v12, 16, v215
	v_and_b32_e32 v13, 0xffff0000, v215
	v_fma_f32 v14, v14, v231, v12
	v_fma_f32 v15, v15, v231, v13
	v_cvt_pk_bf16_f32 v11, v14, v15
	global_store_dword v9, v11, s[62:63]
	v_add_u32_e32 v9, 0x8000, v9
	v_lshlrev_b32_e32 v12, 16, v216
	v_and_b32_e32 v13, 0xffff0000, v216
	v_fma_f32 v14, v14, v232, v12
	v_fma_f32 v15, v15, v232, v13
	v_cvt_pk_bf16_f32 v17, v14, v15
	global_store_dword v9, v17, s[62:63]
	v_add_u32_e32 v9, 0x8000, v9
	v_lshlrev_b32_e32 v12, 16, v217
	v_and_b32_e32 v13, 0xffff0000, v217
	v_fma_f32 v14, v14, v233, v12
	v_fma_f32 v15, v15, v233, v13
	v_cvt_pk_bf16_f32 v11, v14, v15
	global_store_dword v9, v11, s[62:63]
	v_add_u32_e32 v9, 0x8000, v9
	v_lshlrev_b32_e32 v12, 16, v218
	v_and_b32_e32 v13, 0xffff0000, v218
	v_fma_f32 v14, v14, v234, v12
	v_fma_f32 v15, v15, v234, v13
	v_cvt_pk_bf16_f32 v17, v14, v15
	global_store_dword v9, v17, s[62:63]
	v_add_u32_e32 v9, 0x8000, v9
	v_lshlrev_b32_e32 v12, 16, v219
	v_and_b32_e32 v13, 0xffff0000, v219
	v_fma_f32 v14, v14, v235, v12
	v_fma_f32 v15, v15, v235, v13
	v_cvt_pk_bf16_f32 v11, v14, v15
	global_store_dword v9, v11, s[62:63]
	v_add_u32_e32 v9, 0x8000, v9
	v_lshlrev_b32_e32 v12, 16, v220
	v_and_b32_e32 v13, 0xffff0000, v220
	v_fma_f32 v14, v14, v236, v12
	v_fma_f32 v15, v15, v236, v13
	v_cvt_pk_bf16_f32 v17, v14, v15
	global_store_dword v9, v17, s[62:63]
	v_add_u32_e32 v9, 0x8000, v9
	v_lshlrev_b32_e32 v12, 16, v221
	v_and_b32_e32 v13, 0xffff0000, v221
	v_fma_f32 v14, v14, v237, v12
	v_fma_f32 v15, v15, v237, v13
	v_cvt_pk_bf16_f32 v11, v14, v15
	global_store_dword v9, v11, s[62:63]
	v_add_u32_e32 v9, 0x8000, v9
	v_lshlrev_b32_e32 v12, 16, v222
	v_and_b32_e32 v13, 0xffff0000, v222
	v_fma_f32 v14, v14, v238, v12
	v_fma_f32 v15, v15, v238, v13
	v_cvt_pk_bf16_f32 v17, v14, v15
	global_store_dword v9, v17, s[62:63]
	v_lshlrev_b32_e32 v12, 16, v223
	v_and_b32_e32 v13, 0xffff0000, v223
	v_fma_f32 v14, v14, v239, v12
	v_fma_f32 v15, v15, v239, v13
	v_add_u32_e32 v4, s6, v4
	v_lshlrev_b32_e32 v4, 16, v4
	v_lshl_add_u32 v4, v5, 9, v4
	v_lshl_add_u32 v4, v6, 3, v4
	global_store_dwordx2 v4, v[14:15], s[2:3]
	v_add_u32_e32 v16, s10, v16
	v_cmp_lt_i32_e32 vcc, 0x1ffff, v16
	s_or_b64 s[14:15], vcc, s[14:15]
	s_andn2_b64 exec, exec, s[14:15]
	s_cbranch_execnz .Lscan_loop
